# attention O stores widened: 8 dwordx2 -> 4 dwordx4 per lane via v_permlane16_swap row exchange (64 B per row per store)
# speedup vs baseline: 1.0055x; 1.0032x over previous
; __device__ __forceinline__ unsigned cvt_pk_bf16(float lo, float hi) { const f32x2_t f = {lo, hi}; const bf16x2_t b = __builtin_convertvector(f, bf16x2_t); return __builtin_bit_cast(unsigned, b); }
; __device__ __forceinline__ void p4_attn(const Params& p, LAS unsigned char* lds, const int dummy) {
;     ...
;         for (int ps = 0; ps < 5; ++ps) {
;             if (2 * ps + 1 >= ilo) {
;                 u32x4 bw; bw.x = cvt_pk_bf16(sT[2 * ps][0], sT[2 * ps][1]); bw.y = cvt_pk_bf16(sT[2 * ps][2], sT[2 * ps][3]);
;                 if (ps < 4) { bw.z = cvt_pk_bf16(sT[(2 * ps + 1) % 9][0], sT[(2 * ps + 1) % 9][1]); bw.w = cvt_pk_bf16(sT[(2 * ps + 1) % 9][2], sT[(2 * ps + 1) % 9][3]); } else { bw.z = 0u; bw.w = 0u; }
;                 const bf16x8 bfrag = __builtin_bit_cast(bf16x8, bw);
;                 u32x2 vlo[8], vhi[8];
; #pragma unroll
;                 for (int et = 0; et < 8; ++et) {
;                     vlo[et] = tr_read(VB + (16 * (wid + 2 * ps) + 4 * q + (r >> 2)) * VB_STRIDE + (16 * et + 4 * (r & 3)) * 2);
;                     vhi[et] = (u32x2){0u, 0u};
;                     if (ps < 4) vhi[et] = tr_read(VB + (16 * (wid + 2 * ps + 1) + 4 * q + (r >> 2)) * VB_STRIDE + (16 * et + 4 * (r & 3)) * 2);
;                 }
;                 __builtin_amdgcn_sched_barrier(0);
; #pragma unroll
;                 for (int et = 0; et < 8; ++et) {
;                     u32x4 aw; aw.x = vlo[et].x; aw.y = vlo[et].y; aw.z = vhi[et].x; aw.w = vhi[et].y;
;                     oacc[et] = __builtin_amdgcn_mfma_f32_16x16x32_bf16(__builtin_bit_cast(bf16x8, aw), bfrag, oacc[et], 0, 0, 0);
;                 }
;                 __builtin_amdgcn_sched_barrier(0);
;             }
;         }
;         const float rl = 1.0f / lsum;
;         {
;             bf16_t* odst = dummy ? (bf16_t*)((unsigned char*)p.out + 8388608 + ((tq * 1536 + qcol) * 2 & 16777215)) : R1 + tq * QZ_LD + qcol;
; #pragma unroll
;             for (int et = 0; et < 8; ++et) {
;                 u32x2 w; w.x = cvt_pk_bf16(oacc[et][0] * rl, oacc[et][1] * rl); w.y = cvt_pk_bf16(oacc[et][2] * rl, oacc[et][3] * rl);
;                 *(u32x2*)(odst + 16 * et + 4 * q) = w;
;             }
;             if (q == 0) { float2 mlv; mlv.x = mx; mlv.y = lsum; *(float2*)(ML + (tq * 12 + g * 4 + hh) * 2) = mlv; }
.LBB0_626:
	s_add_i32 s98, s98, 1
	ds_read_b64_tr_b16 v[104:105], v197
	ds_read_b64_tr_b16 v[108:109], v197 offset:32
	ds_read_b64_tr_b16 v[202:203], v197 offset:64
	ds_read_b64_tr_b16 v[206:207], v197 offset:96
	ds_read_b64_tr_b16 v[214:215], v197 offset:128
	ds_read_b64_tr_b16 v[218:219], v197 offset:160
	ds_read_b64_tr_b16 v[222:223], v197 offset:192
	ds_read_b64_tr_b16 v[226:227], v197 offset:224
	v_cvt_pk_bf16_f32 v100, v100, v101
	v_cvt_pk_bf16_f32 v101, v102, v103
	v_mov_b32_e32 v102, v36
	v_mov_b32_e32 v103, v36
	v_mov_b32_e32 v106, v36
	v_mov_b32_e32 v107, v36
	v_mov_b32_e32 v110, v36
	v_mov_b32_e32 v111, v36
	v_mov_b32_e32 v204, v36
	v_mov_b32_e32 v205, v36
	v_mov_b32_e32 v208, v36
	v_mov_b32_e32 v209, v36
	v_mov_b32_e32 v216, v36
	v_mov_b32_e32 v217, v36
	v_mov_b32_e32 v220, v36
	v_mov_b32_e32 v221, v36
	v_mov_b32_e32 v224, v36
	v_mov_b32_e32 v225, v36
	v_mov_b32_e32 v228, v36
	v_mov_b32_e32 v229, v36
	s_waitcnt lgkmcnt(7)
	v_mfma_f32_16x16x32_bf16 v[96:99], v[104:107], v[100:103], v[96:99]
	s_waitcnt lgkmcnt(6)
	v_mfma_f32_16x16x32_bf16 v[92:95], v[108:111], v[100:103], v[92:95]
	s_waitcnt lgkmcnt(5)
	v_mfma_f32_16x16x32_bf16 v[88:91], v[202:205], v[100:103], v[88:91]
	s_waitcnt lgkmcnt(4)
	v_mfma_f32_16x16x32_bf16 v[84:87], v[206:209], v[100:103], v[84:87]
	s_waitcnt lgkmcnt(3)
	v_mfma_f32_16x16x32_bf16 v[80:83], v[214:217], v[100:103], v[80:83]
	s_waitcnt lgkmcnt(2)
	v_mfma_f32_16x16x32_bf16 v[76:79], v[218:221], v[100:103], v[76:79]
	s_waitcnt lgkmcnt(1)
	v_mfma_f32_16x16x32_bf16 v[72:75], v[222:225], v[100:103], v[72:75]
	s_waitcnt lgkmcnt(0)
	v_mfma_f32_16x16x32_bf16 v[68:71], v[226:229], v[100:103], v[68:71]
	v_add_f32_e32 v39, v37, v39
	v_div_scale_f32 v37, s[0:1], v39, v39, 1.0
	v_rcp_f32_e32 v100, v37
	v_div_scale_f32 v101, vcc, 1.0, v39, 1.0
	v_mov_b32_e32 v123, v36
	v_fma_f32 v102, -v37, v100, 1.0
	v_fmac_f32_e32 v100, v102, v100
	v_mul_f32_e32 v102, v101, v100
	v_fma_f32 v103, -v37, v102, v101
	v_fmac_f32_e32 v102, v103, v100
	v_fma_f32 v37, -v37, v102, v101
	v_div_fmas_f32 v37, v37, v100, v102
	v_div_fixup_f32 v100, v37, v39, 1.0
	v_pk_mul_f32 v[96:97], v[100:101], v[96:97] op_sel_hi:[0,1]
	v_pk_mul_f32 v[98:99], v[100:101], v[98:99] op_sel_hi:[0,1]
	v_pk_mul_f32 v[92:93], v[100:101], v[92:93] op_sel_hi:[0,1]
	v_pk_mul_f32 v[94:95], v[100:101], v[94:95] op_sel_hi:[0,1]
	v_pk_mul_f32 v[88:89], v[100:101], v[88:89] op_sel_hi:[0,1]
	v_pk_mul_f32 v[90:91], v[100:101], v[90:91] op_sel_hi:[0,1]
	v_pk_mul_f32 v[84:85], v[100:101], v[84:85] op_sel_hi:[0,1]
	v_pk_mul_f32 v[86:87], v[100:101], v[86:87] op_sel_hi:[0,1]
	v_pk_mul_f32 v[80:81], v[100:101], v[80:81] op_sel_hi:[0,1]
	v_pk_mul_f32 v[82:83], v[100:101], v[82:83] op_sel_hi:[0,1]
	v_pk_mul_f32 v[76:77], v[100:101], v[76:77] op_sel_hi:[0,1]
	v_pk_mul_f32 v[78:79], v[100:101], v[78:79] op_sel_hi:[0,1]
	v_pk_mul_f32 v[72:73], v[100:101], v[72:73] op_sel_hi:[0,1]
	v_pk_mul_f32 v[74:75], v[100:101], v[74:75] op_sel_hi:[0,1]
	v_pk_mul_f32 v[68:69], v[100:101], v[68:69] op_sel_hi:[0,1]
	v_pk_mul_f32 v[70:71], v[100:101], v[70:71] op_sel_hi:[0,1]
	v_lshl_add_u64 v[102:103], v[126:127], 0, v[122:123]
	v_cvt_pk_bf16_f32 v96, v96, v97
	v_cvt_pk_bf16_f32 v97, v98, v99
	v_cvt_pk_bf16_f32 v98, v92, v93
	v_cvt_pk_bf16_f32 v99, v94, v95
	v_cvt_pk_bf16_f32 v88, v88, v89
	v_cvt_pk_bf16_f32 v89, v90, v91
	v_cvt_pk_bf16_f32 v90, v84, v85
	v_cvt_pk_bf16_f32 v91, v86, v87
	v_cvt_pk_bf16_f32 v80, v80, v81
	v_cvt_pk_bf16_f32 v81, v82, v83
	v_cvt_pk_bf16_f32 v82, v76, v77
	v_cvt_pk_bf16_f32 v83, v78, v79
	v_cvt_pk_bf16_f32 v72, v72, v73
	v_cvt_pk_bf16_f32 v73, v74, v75
	v_cvt_pk_bf16_f32 v74, v68, v69
	v_cvt_pk_bf16_f32 v75, v70, v71
	v_mbcnt_lo_u32_b32 v92, -1, 0
	v_mbcnt_hi_u32_b32 v92, -1, v92
	v_and_b32_e32 v92, 16, v92
	v_lshrrev_b32_e32 v93, 1, v92
	v_add_u32_e32 v92, v92, v93
	v_mov_b32_e32 v93, 0
	v_permlane16_swap_b32 v96, v98
	v_permlane16_swap_b32 v97, v99
	v_permlane16_swap_b32 v88, v90
	v_permlane16_swap_b32 v89, v91
	v_permlane16_swap_b32 v80, v82
	v_permlane16_swap_b32 v81, v83
	v_permlane16_swap_b32 v72, v74
	v_permlane16_swap_b32 v73, v75
	v_lshl_add_u64 v[102:103], v[102:103], 0, v[92:93]
	s_nop 1
	global_store_dwordx4 v[102:103], v[96:99], off
	global_store_dwordx4 v[102:103], v[88:91], off offset:64
	global_store_dwordx4 v[102:103], v[80:83], off offset:128
	global_store_dwordx4 v[102:103], v[72:75], off offset:192
	s_nop 1
	s_and_saveexec_b64 s[0:1], s[16:17]
	s_cbranch_execz .LBB0_591
	s_lshl_b32 s4, s9, 2
	s_ashr_i32 s5, s4, 31
	v_mov_b32_e32 v68, s4
	v_mov_b32_e32 v69, s5
	v_mad_i64_i32 v[68:69], s[4:5], v124, 12, v[68:69]
	s_mov_b32 s4, s14
	s_mov_b32 s5, s15
	s_mov_b64 s[6:7], s[16:17]
	s_mov_b32 s9, s18
	v_readlane_b32 s12, v254, 29
	v_or_b32_e32 v68, s10, v68
	v_readlane_b32 s14, v254, 31
	v_readlane_b32 s15, v254, 32
	v_readlane_b32 s16, v254, 33
	v_readlane_b32 s17, v254, 34
	v_readlane_b32 s18, v254, 35
	v_readlane_b32 s19, v254, 36
	s_mov_b64 s[16:17], s[6:7]
	s_mov_b32 s15, s5
	s_mov_b32 s14, s4
	v_lshl_add_u64 v[68:69], v[68:69], 3, s[18:19]
	s_mov_b32 s18, s9
	v_readlane_b32 s13, v254, 30
	global_store_dwordx2 v[68:69], v[38:39], off
	s_branch .LBB0_591
